# seam: the XCD's last arriver issues its L2 write-back before the L1/L2 invalidate (invalidate moved behind the cross-XCD add for it; others unchanged)
# baseline (speedup 1.0000x reference)
; __device__ __forceinline__ unsigned xb_ld(unsigned* p)              { return __hip_atomic_load(p, __ATOMIC_RELAXED, __HIP_MEMORY_SCOPE_AGENT); }
; __device__ __forceinline__ unsigned xb_add(unsigned* p, unsigned v) { return __hip_atomic_fetch_add(p, v, __ATOMIC_RELAXED, __HIP_MEMORY_SCOPE_AGENT); }
; #define XB_SPIN(cond, bar) do { unsigned _sp = 0; while (cond) { __builtin_amdgcn_s_sleep(1); \
;     if ((++_sp & 255u) == 0u) { if (xb_ld(&(bar)[XB_TMO])) break; if (_sp > XB_SPIN_CAP) { atomicAdd(&(bar)[XB_TMO], 1u); break; } } } } while (0)
; __device__ __forceinline__ void xcd_barrier(const XcdBarrier& b) {
;     ...
;         const unsigned old = xb_add(&bar[XB_XSUB(b.x)], 1u);
;         const unsigned gen = old / nloc;
;         if (old + 1u == (gen + 1u) * nloc) {
;             __builtin_amdgcn_fence(__ATOMIC_RELEASE, "agent");
;             asm volatile("s_waitcnt vmcnt(0)" ::: "memory");
;             const unsigned og = xb_add(&bar[XB_TOP], 1u);
;             const unsigned tg = og / nx;
;             if (og + 1u == (tg + 1u) * nx) xb_add(&bar[XB_TOPGEN], 1u);
;             else XB_SPIN(xb_ld(&bar[XB_TOPGEN]) == tg, bar);
;             __builtin_amdgcn_fence(__ATOMIC_ACQUIRE, "agent");
;             xb_add(&bar[XB_XGEN(b.x)], 1u);
;             asm volatile("s_waitcnt vmcnt(0)" ::: "memory");
;         } else {
;             XB_SPIN(xb_ld(&bar[XB_XGEN(b.x)]) == gen, bar);
;             __builtin_amdgcn_fence(__ATOMIC_ACQUIRE, "agent");
;             asm volatile("s_waitcnt vmcnt(0)" ::: "memory");
;         }
.Lmy_sm0_have:
	s_add_i32 s100, s100, s9
	s_lshl_b32 s4, s65, 8
	s_addk_i32 s4, 0x1400
	v_mov_b32_e32 v0, s4
	v_mov_b32_e32 v1, 1
	s_waitcnt vmcnt(0) lgkmcnt(0)
	global_atomic_add v1, v0, v1, s[66:67] sc0
	s_waitcnt vmcnt(0)
	v_readfirstlane_b32 s4, v1
	s_add_i32 s4, s4, 1
	s_mul_i32 s4, s4, s9
	s_mul_i32 s5, s100, s8
	s_cmp_lg_u32 s4, s5
	s_cbranch_scc1 .Lmy_sm0_wait
	buffer_wbl2 sc1
	v_mov_b32_e32 v0, 0x3400
	v_mov_b32_e32 v1, s8
	s_waitcnt vmcnt(0)
	global_atomic_add v0, v1, s[66:67]
.Lmy_sm0_wait:
	buffer_inv sc1
	v_mov_b32_e32 v0, 0x3400
	s_mov_b32 s5, 0
